# P7 sample items: wave-0 q-block's q / ssqm loads issued at item start (before staging) instead of after the staging barrier
# baseline (speedup 1.0000x reference)
.LBB0_1052:
	s_cmpk_gt_i32 s31, 0xff
	s_mov_b64 s[26:27], -1
	s_waitcnt vmcnt(0)
	s_cbranch_scc0 .LBB0_1057
	s_add_i32 s2, s31, 0xffffff00
	s_and_b32 s33, s31, 3
	s_lshr_b32 s34, s2, 2
	s_lshl_b32 s26, s34, 17
	s_lshl_b32 s2, s33, 7
	s_or_b32 s26, s26, s2
	v_or_b32_e32 v40, s26, v111
	v_readlane_b32 s36, v246, 6
	v_lshlrev_b64 v[16:17], 2, v[40:41]
	v_readlane_b32 s48, v246, 18
	v_readlane_b32 s49, v246, 19
	v_readlane_b32 s50, v246, 20
	v_readlane_b32 s51, v246, 21
	v_or_b32_e32 v40, s26, v112
	v_lshl_add_u64 v[12:13], s[48:49], 0, v[16:17]
	v_lshl_add_u64 v[16:17], s[50:51], 0, v[16:17]
	v_lshlrev_b64 v[24:25], 2, v[40:41]
	s_barrier
	s_mov_b64 s[56:57], exec
	s_and_b64 exec, exec, s[4:5]
	v_lshl_add_u32 v222, s34, 3, v122
	s_mul_i32 s53, s33, 0x10800
	v_mov_b32_e32 v225, 0
	v_add_u32_e32 v224, s53, v222
	v_lshl_add_u64 v[226:227], v[224:225], 2, s[10:11]
	v_lshlrev_b32_e32 v224, 10, v222
	v_lshl_add_u64 v[228:229], s[8:9], 0, v[224:225]
	s_lshl_b32 s54, s2, 1
	s_mov_b32 s55, 0
	v_lshl_add_u64 v[228:229], v[228:229], 0, s[54:55]
	v_mov_b32_e32 v230, v50
	v_mov_b32_e32 v231, 0
	v_lshl_add_u64 v[228:229], v[228:229], 0, v[230:231]
	s_mov_b64 s[58:59], 0x21000
	v_lshl_add_u64 v[232:233], v[226:227], 0, s[58:59]
	global_load_dwordx4 v[204:207], v[228:229], off nt
	global_load_dwordx4 v[208:211], v[228:229], off offset:64 nt
	global_load_dwordx4 v[212:215], v[228:229], off offset:128 nt
	global_load_dwordx4 v[216:219], v[228:229], off offset:192 nt
	global_load_dword v220, v[226:227], off
	global_load_dword v221, v[232:233], off
	s_mov_b64 exec, s[56:57]
	global_load_dwordx4 v[8:11], v[12:13], off nt
	global_load_dwordx4 v[4:7], v[42:43], off
	global_load_dwordx4 v[0:3], v[42:43], off offset:16
	s_nop 0
	global_load_dwordx4 v[12:15], v[12:13], off offset:16 nt
	s_nop 0
	global_load_dwordx4 v[20:23], v[16:17], off nt
	s_nop 0
	global_load_dwordx4 v[16:19], v[16:17], off offset:16 nt
	v_lshl_add_u64 v[26:27], s[48:49], 0, v[24:25]
	global_load_dwordx4 v[36:39], v[26:27], off nt
	global_load_dwordx4 v[32:35], v[26:27], off offset:16 nt
	v_lshl_add_u64 v[24:25], s[50:51], 0, v[24:25]
	global_load_dwordx4 v[28:31], v[24:25], off nt
	s_nop 0
	global_load_dwordx4 v[24:27], v[24:25], off offset:16 nt
	v_or_b32_e32 v40, s26, v114
	v_lshlrev_b64 v[62:63], 2, v[40:41]
	v_lshl_add_u64 v[58:59], s[48:49], 0, v[62:63]
	global_load_dwordx4 v[54:57], v[58:59], off nt
	s_nop 0
	global_load_dwordx4 v[58:61], v[58:59], off offset:16 nt
	v_or_b32_e32 v40, s26, v115
	v_lshl_add_u64 v[66:67], s[50:51], 0, v[62:63]
	v_lshlrev_b64 v[78:79], 2, v[40:41]
	global_load_dwordx4 v[62:65], v[66:67], off nt
	s_nop 0
	global_load_dwordx4 v[66:69], v[66:67], off offset:16 nt
	v_lshl_add_u64 v[74:75], s[48:49], 0, v[78:79]
	global_load_dwordx4 v[70:73], v[74:75], off nt
	s_nop 0
	global_load_dwordx4 v[74:77], v[74:75], off offset:16 nt
	v_lshl_add_u64 v[82:83], s[50:51], 0, v[78:79]
	v_or_b32_e32 v40, s26, v117
	global_load_dwordx4 v[78:81], v[82:83], off offset:16 nt
	s_nop 0
	global_load_dwordx4 v[82:85], v[82:83], off nt
	v_lshlrev_b64 v[86:87], 2, v[40:41]
	v_or_b32_e32 v40, s26, v118
	v_lshl_add_u64 v[90:91], s[48:49], 0, v[86:87]
	v_lshl_add_u64 v[98:99], s[50:51], 0, v[86:87]
	v_lshlrev_b64 v[102:103], 2, v[40:41]
	v_or_b32_e32 v40, s26, v120
	global_load_dwordx4 v[86:89], v[90:91], off offset:16 nt
	s_nop 0
	global_load_dwordx4 v[90:93], v[90:91], off nt
	s_nop 0
	global_load_dwordx4 v[94:97], v[98:99], off offset:16 nt
	s_nop 0
	global_load_dwordx4 v[98:101], v[98:99], off nt
	v_lshlrev_b64 v[152:153], 2, v[40:41]
	v_lshl_add_u64 v[140:141], s[48:49], 0, v[102:103]
	v_lshl_add_u64 v[148:149], s[50:51], 0, v[102:103]
	v_add_u32_e32 v40, s26, v121
	v_lshl_add_u64 v[156:157], s[48:49], 0, v[152:153]
	v_lshl_add_u64 v[164:165], s[50:51], 0, v[152:153]
	global_load_dwordx4 v[102:105], v[140:141], off offset:16 nt
	s_nop 0
	global_load_dwordx4 v[140:143], v[140:141], off nt
	s_nop 0
	global_load_dwordx4 v[144:147], v[148:149], off offset:16 nt
	s_nop 0
	global_load_dwordx4 v[148:151], v[148:149], off nt
	v_lshlrev_b64 v[168:169], 2, v[40:41]
	global_load_dwordx4 v[152:155], v[156:157], off offset:16 nt
	s_nop 0
	global_load_dwordx4 v[156:159], v[156:157], off nt
	s_nop 0
	global_load_dwordx4 v[160:163], v[164:165], off offset:16 nt
	s_nop 0
	global_load_dwordx4 v[164:167], v[164:165], off nt
	v_readlane_b32 s37, v246, 7
	v_readlane_b32 s38, v246, 8
	v_readlane_b32 s39, v246, 9
	v_readlane_b32 s40, v246, 10
	v_readlane_b32 s41, v246, 11
	v_readlane_b32 s42, v246, 12
	v_readlane_b32 s43, v246, 13
	v_readlane_b32 s44, v246, 14
	v_readlane_b32 s45, v246, 15
	v_readlane_b32 s46, v246, 16
	v_readlane_b32 s47, v246, 17
	s_waitcnt vmcnt(28)
	v_pk_mul_f32 v[170:171], v[6:7], v[10:11]
	v_pk_mul_f32 v[172:173], v[4:5], v[8:9]
	s_waitcnt vmcnt(26)
	v_pk_mul_f32 v[174:175], v[2:3], v[14:15]
	v_pk_mul_f32 v[14:15], v[0:1], v[12:13]
	s_waitcnt vmcnt(25)
	v_cvt_pk_bf16_f32 v8, v20, v21
	v_cvt_pk_bf16_f32 v9, v22, v23
	s_waitcnt vmcnt(24)
	v_cvt_pk_bf16_f32 v10, v16, v17
	v_cvt_pk_bf16_f32 v11, v18, v19
	v_cvt_pk_bf16_f32 v12, v172, v173
	v_cvt_pk_bf16_f32 v13, v170, v171
	v_cvt_pk_bf16_f32 v14, v14, v15
	v_cvt_pk_bf16_f32 v15, v174, v175
	ds_write_b128 v135, v[8:11]
	s_waitcnt vmcnt(23)
	v_pk_mul_f32 v[10:11], v[6:7], v[38:39]
	v_pk_mul_f32 v[8:9], v[4:5], v[36:37]
	s_waitcnt vmcnt(22)
	v_pk_mul_f32 v[16:17], v[2:3], v[34:35]
	v_pk_mul_f32 v[18:19], v[0:1], v[32:33]
	ds_write_b128 v134, v[12:15]
	v_cvt_pk_bf16_f32 v8, v8, v9
	v_cvt_pk_bf16_f32 v9, v10, v11
	v_cvt_pk_bf16_f32 v10, v18, v19
	v_cvt_pk_bf16_f32 v11, v16, v17
	v_lshl_add_u64 v[16:17], s[48:49], 0, v[168:169]
	global_load_dwordx4 v[12:15], v[16:17], off offset:16 nt
	s_nop 0
	global_load_dwordx4 v[16:19], v[16:17], off nt
	ds_write_b128 v134, v[8:11] offset:8704
	s_waitcnt vmcnt(23)
	v_cvt_pk_bf16_f32 v8, v28, v29
	v_cvt_pk_bf16_f32 v9, v30, v31
	s_waitcnt vmcnt(22)
	v_cvt_pk_bf16_f32 v10, v24, v25
	v_cvt_pk_bf16_f32 v11, v26, v27
	ds_write_b128 v135, v[8:11] offset:8704
	v_lshl_add_u64 v[20:21], s[50:51], 0, v[168:169]
	global_load_dwordx4 v[8:11], v[20:21], off offset:16 nt
	s_nop 0
	global_load_dwordx4 v[20:23], v[20:21], off nt
	s_waitcnt vmcnt(23)
	v_pk_mul_f32 v[26:27], v[6:7], v[56:57]
	v_pk_mul_f32 v[24:25], v[4:5], v[54:55]
	s_waitcnt vmcnt(22)
	v_pk_mul_f32 v[28:29], v[2:3], v[60:61]
	v_pk_mul_f32 v[30:31], v[0:1], v[58:59]
	v_cvt_pk_bf16_f32 v24, v24, v25
	v_cvt_pk_bf16_f32 v25, v26, v27
	v_cvt_pk_bf16_f32 v26, v30, v31
	v_cvt_pk_bf16_f32 v27, v28, v29
	ds_write_b128 v134, v[24:27] offset:17408
	s_waitcnt vmcnt(21)
	v_cvt_pk_bf16_f32 v24, v62, v63
	v_cvt_pk_bf16_f32 v25, v64, v65
	s_waitcnt vmcnt(20)
	v_cvt_pk_bf16_f32 v26, v66, v67
	v_cvt_pk_bf16_f32 v27, v68, v69
	ds_write_b128 v135, v[24:27] offset:17408
	s_waitcnt vmcnt(19)
	v_pk_mul_f32 v[26:27], v[6:7], v[72:73]
	v_pk_mul_f32 v[24:25], v[4:5], v[70:71]
	s_waitcnt vmcnt(18)
	v_pk_mul_f32 v[28:29], v[2:3], v[76:77]
	v_pk_mul_f32 v[30:31], v[0:1], v[74:75]
	v_cvt_pk_bf16_f32 v24, v24, v25
	v_cvt_pk_bf16_f32 v25, v26, v27
	v_cvt_pk_bf16_f32 v26, v30, v31
	v_cvt_pk_bf16_f32 v27, v28, v29
	ds_write_b128 v134, v[24:27] offset:26112
	s_waitcnt vmcnt(16)
	v_cvt_pk_bf16_f32 v24, v82, v83
	v_cvt_pk_bf16_f32 v25, v84, v85
	v_cvt_pk_bf16_f32 v26, v78, v79
	v_cvt_pk_bf16_f32 v27, v80, v81
	ds_write_b128 v135, v[24:27] offset:26112
	s_waitcnt vmcnt(14)
	v_pk_mul_f32 v[26:27], v[6:7], v[92:93]
	v_pk_mul_f32 v[24:25], v[4:5], v[90:91]
	v_pk_mul_f32 v[28:29], v[2:3], v[88:89]
	v_pk_mul_f32 v[30:31], v[0:1], v[86:87]
	v_cvt_pk_bf16_f32 v24, v24, v25
	v_cvt_pk_bf16_f32 v25, v26, v27
	v_cvt_pk_bf16_f32 v26, v30, v31
	v_cvt_pk_bf16_f32 v27, v28, v29
	ds_write_b128 v134, v[24:27] offset:34816
	s_waitcnt vmcnt(12)
	v_cvt_pk_bf16_f32 v24, v98, v99
	v_cvt_pk_bf16_f32 v25, v100, v101
	v_cvt_pk_bf16_f32 v26, v94, v95
	v_cvt_pk_bf16_f32 v27, v96, v97
	ds_write_b128 v135, v[24:27] offset:34816
	s_waitcnt vmcnt(10)
	v_pk_mul_f32 v[26:27], v[6:7], v[142:143]
	v_pk_mul_f32 v[24:25], v[4:5], v[140:141]
	v_pk_mul_f32 v[28:29], v[2:3], v[104:105]
	v_pk_mul_f32 v[30:31], v[0:1], v[102:103]
	v_cvt_pk_bf16_f32 v24, v24, v25
	v_cvt_pk_bf16_f32 v25, v26, v27
	v_cvt_pk_bf16_f32 v26, v30, v31
	v_cvt_pk_bf16_f32 v27, v28, v29
	ds_write_b128 v134, v[24:27] offset:43520
	s_waitcnt vmcnt(8)
	v_cvt_pk_bf16_f32 v24, v148, v149
	v_cvt_pk_bf16_f32 v25, v150, v151
	v_cvt_pk_bf16_f32 v26, v144, v145
	v_cvt_pk_bf16_f32 v27, v146, v147
	ds_write_b128 v135, v[24:27] offset:43520
	s_waitcnt vmcnt(6)
	v_pk_mul_f32 v[26:27], v[6:7], v[158:159]
	v_pk_mul_f32 v[24:25], v[4:5], v[156:157]
	v_pk_mul_f32 v[28:29], v[2:3], v[154:155]
	v_pk_mul_f32 v[30:31], v[0:1], v[152:153]
	v_cvt_pk_bf16_f32 v24, v24, v25
	v_cvt_pk_bf16_f32 v25, v26, v27
	v_cvt_pk_bf16_f32 v26, v30, v31
	v_cvt_pk_bf16_f32 v27, v28, v29
	ds_write_b128 v134, v[24:27] offset:52224
	s_waitcnt vmcnt(4)
	v_cvt_pk_bf16_f32 v24, v164, v165
	v_cvt_pk_bf16_f32 v25, v166, v167
	v_cvt_pk_bf16_f32 v26, v160, v161
	v_cvt_pk_bf16_f32 v27, v162, v163
	ds_write_b128 v135, v[24:27] offset:52224
	s_waitcnt vmcnt(3)
	v_pk_mul_f32 v[14:15], v[2:3], v[14:15]
	s_waitcnt vmcnt(2)
	v_pk_mul_f32 v[6:7], v[6:7], v[18:19]
	v_pk_mul_f32 v[4:5], v[4:5], v[16:17]
	v_pk_mul_f32 v[2:3], v[0:1], v[12:13]
	v_cvt_pk_bf16_f32 v0, v4, v5
	v_cvt_pk_bf16_f32 v1, v6, v7
	v_cvt_pk_bf16_f32 v2, v2, v3
	v_cvt_pk_bf16_f32 v3, v14, v15
	ds_write_b128 v134, v[0:3] offset:60928
	s_waitcnt vmcnt(0)
	v_cvt_pk_bf16_f32 v0, v20, v21
	v_cvt_pk_bf16_f32 v1, v22, v23
	v_cvt_pk_bf16_f32 v2, v8, v9
	v_cvt_pk_bf16_f32 v3, v10, v11
	ds_write_b128 v135, v[0:3] offset:60928
	s_waitcnt lgkmcnt(0)
	s_barrier
	s_and_saveexec_b64 s[26:27], s[4:5]
	s_cbranch_execz .LBB0_1056
	v_lshl_add_u32 v53, s34, 3, v122
	s_mul_i32 s33, s33, 0x10800
	v_add_u32_e32 v40, s33, v53
	v_lshl_add_u64 v[28:29], v[40:41], 2, s[10:11]
	v_lshlrev_b32_e32 v40, 10, v53
	v_lshl_add_u64 v[0:1], s[8:9], 0, v[40:41]
	s_lshl_b32 s2, s2, 1
	v_lshl_add_u64 v[0:1], v[0:1], 0, s[2:3]
	v_mov_b32_e32 v51, v41
	v_lshl_add_u64 v[30:31], v[0:1], 0, v[50:51]
	v_mov_b32_e32 v8, v204
	v_mov_b32_e32 v9, v205
	v_mov_b32_e32 v10, v206
	v_mov_b32_e32 v11, v207
	v_mov_b32_e32 v0, v208
	v_mov_b32_e32 v1, v209
	v_mov_b32_e32 v2, v210
	v_mov_b32_e32 v3, v211
	v_mov_b32_e32 v4, v212
	v_mov_b32_e32 v5, v213
	v_mov_b32_e32 v6, v214
	v_mov_b32_e32 v7, v215
	ds_read_b128 v[12:15], v123
	v_add_co_u32_e32 v32, vcc, 0x21000, v28
	ds_read_b128 v[16:19], v123 offset:64
	ds_read_b128 v[20:23], v123 offset:4352
	v_addc_co_u32_e32 v33, vcc, 0, v29, vcc
	v_mov_b32_e32 v34, v220
	v_mov_b32_e32 v32, v221
	s_waitcnt lgkmcnt(2)
	v_mfma_f32_16x16x32_bf16 v[24:27], v[12:15], v[8:11], 0
	v_add_f32_e32 v32, v34, v32
	s_waitcnt lgkmcnt(1)
	v_mfma_f32_16x16x32_bf16 v[16:19], v[16:19], v[0:3], v[24:27]
	v_fmamk_f32 v32, v32, 0x3c000000, v136
	s_nop 1
	ds_read_b128 v[24:27], v123 offset:4416
	s_waitcnt lgkmcnt(1)
	v_mfma_f32_16x16x32_bf16 v[20:23], v[20:23], v[8:11], 0
	s_waitcnt lgkmcnt(0)
	v_mfma_f32_16x16x32_bf16 v[20:23], v[24:27], v[0:3], v[20:23]
	ds_read_b128 v[24:27], v123 offset:128
	ds_read_b128 v[28:31], v123 offset:192
	s_waitcnt lgkmcnt(1)
	v_mfma_f32_16x16x32_bf16 v[16:19], v[24:27], v[4:7], v[16:19]
	ds_read_b128 v[24:27], v123 offset:4480
	s_waitcnt lgkmcnt(0)
	v_mfma_f32_16x16x32_bf16 v[20:23], v[24:27], v[4:7], v[20:23]
	ds_read_b128 v[24:27], v123 offset:4544
	v_mfma_f32_16x16x32_bf16 v[16:19], v[28:31], v[216:219], v[16:19]
	v_rsq_f32_e32 v28, v32
	s_nop 0
	v_mul_f32_e32 v40, 0x3e0293ee, v28
	s_waitcnt lgkmcnt(0)
	v_mfma_f32_16x16x32_bf16 v[24:27], v[24:27], v[216:219], v[20:23]
	s_nop 2
	v_mul_f32_e64 v30, v40, v16
	v_mul_f32_e64 v31, v40, v17
	v_pk_mul_f32 v[22:23], v[40:41], v[18:19] op_sel_hi:[0,1]
	s_nop 1
	v_pk_mul_f32 v[16:17], v[40:41], v[26:27] op_sel_hi:[0,1]
	v_pk_mul_f32 v[20:21], v[40:41], v[24:25] op_sel_hi:[0,1]
	ds_read_b128 v[24:27], v123 offset:8704
	ds_read_b128 v[32:35], v123 offset:8768
	ds_read_b128 v[54:57], v123 offset:8832
	ds_read_b128 v[36:39], v123 offset:13056
	s_waitcnt lgkmcnt(3)
	v_mfma_f32_16x16x32_bf16 v[24:27], v[24:27], v[8:11], 0
	s_waitcnt lgkmcnt(2)
	v_mfma_f32_16x16x32_bf16 v[24:27], v[32:35], v[0:3], v[24:27]
	ds_read_b128 v[32:35], v123 offset:8896
	s_waitcnt lgkmcnt(2)
	v_mfma_f32_16x16x32_bf16 v[24:27], v[54:57], v[4:7], v[24:27]
	ds_read_b128 v[54:57], v123 offset:13248
	s_waitcnt lgkmcnt(1)
	v_mfma_f32_16x16x32_bf16 v[24:27], v[32:35], v[216:219], v[24:27]
	ds_read_b128 v[32:35], v123 offset:13120
	v_mfma_f32_16x16x32_bf16 v[36:39], v[36:39], v[8:11], 0
	s_nop 5
	v_mul_f32_e64 v28, v40, v26
	v_mul_f32_e64 v29, v40, v27
	s_waitcnt lgkmcnt(0)
	v_mfma_f32_16x16x32_bf16 v[32:35], v[32:35], v[0:3], v[36:39]
	s_nop 2
	ds_read_b128 v[36:39], v123 offset:13184
	s_waitcnt lgkmcnt(0)
	v_mfma_f32_16x16x32_bf16 v[32:35], v[36:39], v[4:7], v[32:35]
	v_mul_f32_e64 v38, v40, v24
	v_mul_f32_e64 v39, v40, v25
	v_mfma_f32_16x16x32_bf16 v[24:27], v[54:57], v[216:219], v[32:35]
	s_nop 7
	v_pk_mul_f32 v[18:19], v[40:41], v[26:27] op_sel_hi:[0,1]
	v_pk_mul_f32 v[26:27], v[40:41], v[24:25] op_sel_hi:[0,1]
	ds_read_b128 v[32:35], v123 offset:17408
	ds_read_b128 v[54:57], v123 offset:17472
	ds_read_b128 v[62:65], v123 offset:17536
	ds_read_b128 v[58:61], v123 offset:21760
	s_waitcnt lgkmcnt(3)
	v_mfma_f32_16x16x32_bf16 v[32:35], v[32:35], v[8:11], 0
	s_waitcnt lgkmcnt(2)
	v_mfma_f32_16x16x32_bf16 v[32:35], v[54:57], v[0:3], v[32:35]
	ds_read_b128 v[54:57], v123 offset:17600
	s_waitcnt lgkmcnt(2)
	v_mfma_f32_16x16x32_bf16 v[32:35], v[62:65], v[4:7], v[32:35]
	ds_read_b128 v[62:65], v123 offset:21952
	s_waitcnt lgkmcnt(1)
	v_mfma_f32_16x16x32_bf16 v[32:35], v[54:57], v[216:219], v[32:35]
	ds_read_b128 v[54:57], v123 offset:21824
	v_mfma_f32_16x16x32_bf16 v[58:61], v[58:61], v[8:11], 0
	s_nop 5
	v_mul_f32_e64 v36, v40, v34
	v_mul_f32_e64 v37, v40, v35
	s_waitcnt lgkmcnt(0)
	v_mfma_f32_16x16x32_bf16 v[54:57], v[54:57], v[0:3], v[58:61]
	s_nop 2
	ds_read_b128 v[58:61], v123 offset:21888
	s_waitcnt lgkmcnt(0)
	v_mfma_f32_16x16x32_bf16 v[58:61], v[58:61], v[4:7], v[54:57]
	s_nop 2
	v_mul_f32_e64 v56, v40, v32
	v_mul_f32_e64 v57, v40, v33
	v_mfma_f32_16x16x32_bf16 v[32:35], v[62:65], v[216:219], v[58:61]
	s_nop 7
	v_pk_mul_f32 v[24:25], v[40:41], v[34:35] op_sel_hi:[0,1]
	v_pk_mul_f32 v[34:35], v[40:41], v[32:33] op_sel_hi:[0,1]
	ds_read_b128 v[58:61], v123 offset:26112
	ds_read_b128 v[62:65], v123 offset:26176
	ds_read_b128 v[70:73], v123 offset:26240
	ds_read_b128 v[66:69], v123 offset:30464
	s_waitcnt lgkmcnt(3)
	v_mfma_f32_16x16x32_bf16 v[58:61], v[58:61], v[8:11], 0
	s_waitcnt lgkmcnt(2)
	v_mfma_f32_16x16x32_bf16 v[58:61], v[62:65], v[0:3], v[58:61]
	ds_read_b128 v[62:65], v123 offset:26304
	s_waitcnt lgkmcnt(2)
	v_mfma_f32_16x16x32_bf16 v[58:61], v[70:73], v[4:7], v[58:61]
	s_waitcnt lgkmcnt(0)
	v_mfma_f32_16x16x32_bf16 v[58:61], v[62:65], v[216:219], v[58:61]
	ds_read_b128 v[62:65], v123 offset:30528
	v_mfma_f32_16x16x32_bf16 v[66:69], v[66:69], v[8:11], 0
	s_nop 5
	v_mul_f32_e64 v76, v40, v58
	v_mul_f32_e64 v77, v40, v59
	s_waitcnt lgkmcnt(0)
	v_mfma_f32_16x16x32_bf16 v[62:65], v[62:65], v[0:3], v[66:69]
	s_nop 2
	ds_read_b128 v[66:69], v123 offset:30592
	s_waitcnt lgkmcnt(0)
	v_mfma_f32_16x16x32_bf16 v[62:65], v[66:69], v[4:7], v[62:65]
	ds_read_b128 v[68:71], v123 offset:30656
	v_pk_mul_f32 v[66:67], v[40:41], v[60:61] op_sel_hi:[0,1]
	s_waitcnt lgkmcnt(0)
	v_mfma_f32_16x16x32_bf16 v[58:61], v[68:71], v[216:219], v[62:65]
	s_nop 7
	v_pk_mul_f32 v[32:33], v[40:41], v[60:61] op_sel_hi:[0,1]
	v_pk_mul_f32 v[54:55], v[40:41], v[58:59] op_sel_hi:[0,1]
	ds_read_b128 v[58:61], v123 offset:34816
	ds_read_b128 v[62:65], v123 offset:34880
	ds_read_b128 v[72:75], v123 offset:34944
	ds_read_b128 v[68:71], v123 offset:39168
	s_waitcnt lgkmcnt(3)
	v_mfma_f32_16x16x32_bf16 v[58:61], v[58:61], v[8:11], 0
	s_waitcnt lgkmcnt(2)
	v_mfma_f32_16x16x32_bf16 v[58:61], v[62:65], v[0:3], v[58:61]
	ds_read_b128 v[62:65], v123 offset:35008
	s_waitcnt lgkmcnt(2)
	v_mfma_f32_16x16x32_bf16 v[58:61], v[72:75], v[4:7], v[58:61]
	s_waitcnt lgkmcnt(0)
	v_mfma_f32_16x16x32_bf16 v[58:61], v[62:65], v[216:219], v[58:61]
	ds_read_b128 v[62:65], v123 offset:39232
	v_mfma_f32_16x16x32_bf16 v[68:71], v[68:71], v[8:11], 0
	s_nop 5
	v_mul_f32_e64 v74, v40, v60
	v_mul_f32_e64 v75, v40, v61
	v_pk_mul_f32 v[84:85], v[40:41], v[58:59] op_sel_hi:[0,1]
	s_waitcnt lgkmcnt(0)
	v_mfma_f32_16x16x32_bf16 v[62:65], v[62:65], v[0:3], v[68:71]
	s_nop 2
	ds_read_b128 v[68:71], v123 offset:39296
	s_waitcnt lgkmcnt(0)
	v_mfma_f32_16x16x32_bf16 v[62:65], v[68:71], v[4:7], v[62:65]
	ds_read_b128 v[68:71], v123 offset:39360
	s_waitcnt lgkmcnt(0)
	v_mfma_f32_16x16x32_bf16 v[58:61], v[68:71], v[216:219], v[62:65]
	s_nop 7
	v_pk_mul_f32 v[64:65], v[40:41], v[60:61] op_sel_hi:[0,1]
	v_pk_mul_f32 v[70:71], v[40:41], v[58:59] op_sel_hi:[0,1]
	ds_read_b128 v[58:61], v123 offset:43520
	ds_read_b128 v[78:81], v123 offset:43584
	ds_read_b128 v[90:93], v123 offset:43648
	ds_read_b128 v[86:89], v123 offset:47872
	s_waitcnt lgkmcnt(3)
	v_mfma_f32_16x16x32_bf16 v[58:61], v[58:61], v[8:11], 0
	s_waitcnt lgkmcnt(2)
	v_mfma_f32_16x16x32_bf16 v[58:61], v[78:81], v[0:3], v[58:61]
	ds_read_b128 v[78:81], v123 offset:43712
	s_waitcnt lgkmcnt(2)
	v_mfma_f32_16x16x32_bf16 v[58:61], v[90:93], v[4:7], v[58:61]
	s_waitcnt lgkmcnt(0)
	v_mfma_f32_16x16x32_bf16 v[58:61], v[78:81], v[216:219], v[58:61]
	ds_read_b128 v[78:81], v123 offset:47936
	v_mfma_f32_16x16x32_bf16 v[86:89], v[86:89], v[8:11], 0
	s_nop 5
	v_mul_f32_e64 v82, v40, v60
	v_mul_f32_e64 v83, v40, v61
	v_pk_mul_f32 v[94:95], v[40:41], v[58:59] op_sel_hi:[0,1]
	s_waitcnt lgkmcnt(0)
	v_mfma_f32_16x16x32_bf16 v[78:81], v[78:81], v[0:3], v[86:89]
	s_nop 2
	ds_read_b128 v[86:89], v123 offset:48000
	s_waitcnt lgkmcnt(0)
	v_mfma_f32_16x16x32_bf16 v[78:81], v[86:89], v[4:7], v[78:81]
	ds_read_b128 v[86:89], v123 offset:48064
	s_waitcnt lgkmcnt(0)
	v_mfma_f32_16x16x32_bf16 v[58:61], v[86:89], v[216:219], v[78:81]
	s_nop 7
	v_pk_mul_f32 v[68:69], v[40:41], v[60:61] op_sel_hi:[0,1]
	v_pk_mul_f32 v[80:81], v[40:41], v[58:59] op_sel_hi:[0,1]
	ds_read_b128 v[58:61], v123 offset:52224
	ds_read_b128 v[86:89], v123 offset:52288
	ds_read_b128 v[96:99], v123 offset:52352
	ds_read_b128 v[90:93], v123 offset:56576
	s_waitcnt lgkmcnt(3)
	v_mfma_f32_16x16x32_bf16 v[58:61], v[58:61], v[8:11], 0
	ds_read_b128 v[100:103], v123 offset:56768
	s_waitcnt lgkmcnt(3)
	v_mfma_f32_16x16x32_bf16 v[58:61], v[86:89], v[0:3], v[58:61]
	ds_read_b128 v[86:89], v123 offset:52416
	s_waitcnt lgkmcnt(3)
	v_mfma_f32_16x16x32_bf16 v[58:61], v[96:99], v[4:7], v[58:61]
	s_waitcnt lgkmcnt(0)
	v_mfma_f32_16x16x32_bf16 v[58:61], v[86:89], v[216:219], v[58:61]
	ds_read_b128 v[86:89], v123 offset:56640
	v_mfma_f32_16x16x32_bf16 v[90:93], v[90:93], v[8:11], 0
	s_nop 5
	v_mul_f32_e64 v98, v40, v58
	v_mul_f32_e64 v99, v40, v59
	s_waitcnt lgkmcnt(0)
	v_mfma_f32_16x16x32_bf16 v[86:89], v[86:89], v[0:3], v[90:93]
	s_nop 2
	ds_read_b128 v[90:93], v123 offset:56704
	s_waitcnt lgkmcnt(0)
	v_mfma_f32_16x16x32_bf16 v[86:89], v[90:93], v[4:7], v[86:89]
	v_mul_f32_e64 v92, v40, v60
	v_mul_f32_e64 v93, v40, v61
	v_mfma_f32_16x16x32_bf16 v[58:61], v[100:103], v[216:219], v[86:89]
	s_nop 7
	v_pk_mul_f32 v[78:79], v[40:41], v[60:61] op_sel_hi:[0,1]
	v_pk_mul_f32 v[90:91], v[40:41], v[58:59] op_sel_hi:[0,1]
	ds_read_b128 v[58:61], v123 offset:60928
	ds_read_b128 v[86:89], v123 offset:60992
	ds_read_b128 v[100:103], v123 offset:65280
	s_waitcnt lgkmcnt(2)
	v_mfma_f32_16x16x32_bf16 v[58:61], v[58:61], v[8:11], 0
	s_waitcnt lgkmcnt(1)
	v_mfma_f32_16x16x32_bf16 v[58:61], v[86:89], v[0:3], v[58:61]
	ds_read_b128 v[86:89], v123 offset:61120
	s_waitcnt lgkmcnt(1)
	v_mfma_f32_16x16x32_bf16 v[8:11], v[100:103], v[8:11], 0
	ds_read_b128 v[100:103], v123 offset:61056
	s_waitcnt lgkmcnt(0)
	v_mfma_f32_16x16x32_bf16 v[58:61], v[100:103], v[4:7], v[58:61]
	v_mfma_f32_16x16x32_bf16 v[58:61], v[86:89], v[216:219], v[58:61]
	ds_read_b128 v[86:89], v123 offset:65344
	s_waitcnt lgkmcnt(0)
	v_mfma_f32_16x16x32_bf16 v[0:3], v[86:89], v[0:3], v[8:11]
	s_nop 2
	ds_read_b128 v[8:11], v123 offset:65408
	ds_read_b128 v[86:89], v123 offset:65472
	s_waitcnt lgkmcnt(1)
	v_mfma_f32_16x16x32_bf16 v[6:9], v[8:11], v[4:7], v[0:3]
	v_mul_f32_e64 v4, v40, v60
	v_mul_f32_e64 v5, v40, v61
	s_nop 0
	v_pk_mul_f32 v[0:1], v[40:41], v[58:59] op_sel_hi:[0,1]
	s_waitcnt lgkmcnt(0)
	v_mfma_f32_16x16x32_bf16 v[8:11], v[86:89], v[216:219], v[6:9]
	s_nop 7
	v_pk_mul_f32 v[6:7], v[40:41], v[10:11] op_sel_hi:[0,1]
	v_pk_mul_f32 v[2:3], v[40:41], v[8:9] op_sel_hi:[0,1]
	v_max_f32_e32 v8, v30, v31
	v_max_f32_e32 v9, v22, v23
	v_max3_f32 v8, v8, s30, v9
	v_max_f32_e32 v9, v20, v21
	v_max_f32_e32 v10, v16, v17
	v_max3_f32 v8, v8, v9, v10
	v_max_f32_e32 v9, v38, v39
	v_max_f32_e32 v10, v28, v29
	v_max3_f32 v8, v8, v9, v10
	v_max_f32_e32 v9, v26, v27
	v_max_f32_e32 v10, v18, v19
	v_max3_f32 v8, v8, v9, v10
	v_max_f32_e32 v9, v56, v57
	v_max_f32_e32 v10, v36, v37
	v_max3_f32 v8, v8, v9, v10
	v_max_f32_e32 v9, v34, v35
	v_max_f32_e32 v10, v24, v25
	v_max3_f32 v8, v8, v9, v10
	v_max_f32_e32 v9, v76, v77
	v_max_f32_e32 v10, v66, v67
	v_max3_f32 v8, v8, v9, v10
	v_max_f32_e32 v9, v54, v55
	v_max_f32_e32 v10, v32, v33
	v_max3_f32 v8, v8, v9, v10
	v_max_f32_e32 v9, v84, v85
	v_max_f32_e32 v10, v74, v75
	v_max3_f32 v8, v8, v9, v10
	v_max_f32_e32 v9, v70, v71
	v_max_f32_e32 v10, v64, v65
	v_max3_f32 v8, v8, v9, v10
	v_max_f32_e32 v9, v94, v95
	v_max_f32_e32 v10, v82, v83
	v_max3_f32 v8, v8, v9, v10
	v_max_f32_e32 v9, v80, v81
	v_max_f32_e32 v10, v68, v69
	v_max3_f32 v8, v8, v9, v10
	v_max_f32_e32 v9, v98, v99
	v_max_f32_e32 v10, v92, v93
	v_max3_f32 v8, v8, v9, v10
	v_max_f32_e32 v9, v90, v91
	v_max_f32_e32 v10, v78, v79
	v_max3_f32 v8, v8, v9, v10
	v_max_f32_e32 v9, v0, v1
	v_max_f32_e32 v10, v4, v5
	v_max3_f32 v8, v8, v9, v10
	v_max_f32_e32 v9, v2, v3
	v_max_f32_e32 v10, v6, v7
	v_max3_f32 v8, v8, v9, v10
	v_and_b32_e32 v10, 64, v137
	v_xor_b32_e32 v9, 16, v137
	v_add_u32_e32 v10, 64, v10
	v_cmp_lt_i32_e32 vcc, v9, v10
	s_nop 1
	v_cndmask_b32_e32 v9, v137, v9, vcc
	v_lshlrev_b32_e32 v9, 2, v9
	ds_bpermute_b32 v11, v9, v8
	s_waitcnt lgkmcnt(0)
	v_max_f32_e32 v11, v11, v11
	v_max_f32_e32 v8, v8, v11
	v_xor_b32_e32 v11, 32, v137
	v_cmp_lt_i32_e32 vcc, v11, v10
	s_nop 1
	v_cndmask_b32_e32 v10, v137, v11, vcc
	v_lshlrev_b32_e32 v40, 2, v10
	ds_bpermute_b32 v10, v40, v8
	s_waitcnt lgkmcnt(0)
	v_max_f32_e32 v10, v10, v10
	v_max_f32_e32 v8, v8, v10
	v_sub_f32_e32 v10, v30, v8
	v_exp_f32_e32 v100, v10
	v_sub_f32_e32 v10, v31, v8
	v_exp_f32_e32 v101, v10
	v_sub_f32_e32 v10, v22, v8
	v_exp_f32_e32 v102, v10
	v_sub_f32_e32 v10, v23, v8
	v_exp_f32_e32 v103, v10
	v_sub_f32_e32 v11, v20, v8
	v_add_f32_e32 v10, 0, v100
	v_exp_f32_e32 v104, v11
	v_sub_f32_e32 v11, v21, v8
	v_add_f32_e32 v10, v101, v10
	v_exp_f32_e32 v105, v11
	v_sub_f32_e32 v11, v16, v8
	v_add_f32_e32 v10, v102, v10
	v_exp_f32_e32 v140, v11
	v_sub_f32_e32 v11, v17, v8
	v_add_f32_e32 v10, v103, v10
	v_exp_f32_e32 v141, v11
	v_sub_f32_e32 v11, v38, v8
	v_add_f32_e32 v10, v104, v10
	v_exp_f32_e32 v72, v11
	v_sub_f32_e32 v11, v39, v8
	v_add_f32_e32 v10, v105, v10
	v_exp_f32_e32 v73, v11
	v_sub_f32_e32 v11, v28, v8
	v_add_f32_e32 v10, v140, v10
	v_exp_f32_e32 v88, v11
	v_sub_f32_e32 v11, v29, v8
	v_add_f32_e32 v10, v141, v10
	v_exp_f32_e32 v89, v11
	v_sub_f32_e32 v11, v26, v8
	v_add_f32_e32 v10, v72, v10
	v_exp_f32_e32 v86, v11
	v_sub_f32_e32 v11, v27, v8
	v_add_f32_e32 v10, v73, v10
	v_exp_f32_e32 v87, v11
	v_sub_f32_e32 v11, v18, v8
	v_add_f32_e32 v10, v88, v10
	v_exp_f32_e32 v96, v11
	v_sub_f32_e32 v11, v19, v8
	v_add_f32_e32 v10, v89, v10
	v_exp_f32_e32 v97, v11
	v_sub_f32_e32 v11, v56, v8
	v_add_f32_e32 v10, v86, v10
	v_exp_f32_e32 v56, v11
	v_sub_f32_e32 v11, v57, v8
	v_add_f32_e32 v10, v87, v10
	v_exp_f32_e32 v57, v11
	v_sub_f32_e32 v11, v36, v8
	v_add_f32_e32 v10, v96, v10
	v_exp_f32_e32 v60, v11
	v_sub_f32_e32 v11, v37, v8
	v_add_f32_e32 v10, v97, v10
	v_exp_f32_e32 v61, v11
	v_sub_f32_e32 v11, v34, v8
	v_add_f32_e32 v10, v56, v10
	v_exp_f32_e32 v58, v11
	v_sub_f32_e32 v11, v35, v8
	v_add_f32_e32 v10, v57, v10
	v_exp_f32_e32 v59, v11
	v_sub_f32_e32 v11, v24, v8
	v_add_f32_e32 v10, v60, v10
	v_exp_f32_e32 v62, v11
	v_sub_f32_e32 v11, v25, v8
	v_add_f32_e32 v10, v61, v10
	v_exp_f32_e32 v63, v11
	v_sub_f32_e32 v11, v76, v8
	v_add_f32_e32 v10, v58, v10
	v_exp_f32_e32 v34, v11
	v_sub_f32_e32 v11, v77, v8
	v_add_f32_e32 v10, v59, v10
	v_exp_f32_e32 v35, v11
	v_sub_f32_e32 v11, v66, v8
	v_add_f32_e32 v10, v62, v10
	v_exp_f32_e32 v38, v11
	v_sub_f32_e32 v11, v67, v8
	v_add_f32_e32 v10, v63, v10
	v_exp_f32_e32 v39, v11
	v_sub_f32_e32 v11, v54, v8
	v_add_f32_e32 v10, v34, v10
	v_exp_f32_e32 v36, v11
	v_sub_f32_e32 v11, v55, v8
	v_add_f32_e32 v10, v35, v10
	v_exp_f32_e32 v37, v11
	v_sub_f32_e32 v11, v32, v8
	v_add_f32_e32 v10, v38, v10
	v_exp_f32_e32 v54, v11
	v_sub_f32_e32 v11, v33, v8
	v_add_f32_e32 v10, v39, v10
	v_exp_f32_e32 v55, v11
	v_sub_f32_e32 v11, v84, v8
	v_add_f32_e32 v10, v36, v10
	v_exp_f32_e32 v26, v11
	v_sub_f32_e32 v11, v85, v8
	v_add_f32_e32 v10, v37, v10
	v_exp_f32_e32 v27, v11
	v_sub_f32_e32 v11, v74, v8
	v_add_f32_e32 v10, v54, v10
	v_exp_f32_e32 v30, v11
	v_sub_f32_e32 v11, v75, v8
	v_add_f32_e32 v10, v55, v10
	v_exp_f32_e32 v31, v11
	v_sub_f32_e32 v11, v70, v8
	v_add_f32_e32 v10, v26, v10
	v_exp_f32_e32 v28, v11
	v_sub_f32_e32 v11, v71, v8
	v_add_f32_e32 v10, v27, v10
	v_exp_f32_e32 v29, v11
	v_sub_f32_e32 v11, v64, v8
	v_add_f32_e32 v10, v30, v10
	v_exp_f32_e32 v32, v11
	v_sub_f32_e32 v11, v65, v8
	v_add_f32_e32 v10, v31, v10
	v_exp_f32_e32 v33, v11
	v_sub_f32_e32 v11, v94, v8
	v_add_f32_e32 v10, v28, v10
	v_exp_f32_e32 v18, v11
	v_sub_f32_e32 v11, v95, v8
	v_add_f32_e32 v10, v29, v10
	v_exp_f32_e32 v19, v11
	v_sub_f32_e32 v11, v82, v8
	v_add_f32_e32 v10, v32, v10
	v_exp_f32_e32 v22, v11
	v_sub_f32_e32 v11, v83, v8
	v_add_f32_e32 v10, v33, v10
	v_exp_f32_e32 v23, v11
	v_sub_f32_e32 v11, v80, v8
	v_add_f32_e32 v10, v18, v10
	v_exp_f32_e32 v20, v11
	v_sub_f32_e32 v11, v81, v8
	v_add_f32_e32 v10, v19, v10
	v_exp_f32_e32 v21, v11
	v_sub_f32_e32 v11, v68, v8
	v_add_f32_e32 v10, v22, v10
	v_exp_f32_e32 v24, v11
	v_sub_f32_e32 v11, v69, v8
	v_add_f32_e32 v10, v23, v10
	v_exp_f32_e32 v25, v11
	v_add_f32_e32 v10, v20, v10
	v_add_f32_e32 v10, v21, v10
	v_add_f32_e32 v10, v24, v10
	v_add_f32_e32 v12, v25, v10
	v_sub_f32_e32 v10, v98, v8
	v_exp_f32_e32 v10, v10
	v_sub_f32_e32 v11, v99, v8
	v_exp_f32_e32 v11, v11
	v_sub_f32_e32 v13, v92, v8
	v_exp_f32_e32 v14, v13
	v_sub_f32_e32 v13, v93, v8
	v_exp_f32_e32 v15, v13
	v_add_f32_e32 v12, v10, v12
	v_add_f32_e32 v12, v11, v12
	v_add_f32_e32 v12, v14, v12
	v_add_f32_e32 v51, v15, v12
	v_sub_f32_e32 v12, v90, v8
	v_exp_f32_e32 v12, v12
	v_sub_f32_e32 v13, v91, v8
	v_exp_f32_e32 v13, v13
	v_sub_f32_e32 v16, v78, v8
	v_exp_f32_e32 v16, v16
	v_sub_f32_e32 v17, v79, v8
	v_exp_f32_e32 v17, v17
	v_sub_f32_e32 v0, v0, v8
	v_add_f32_e32 v51, v12, v51
	v_exp_f32_e32 v0, v0
	v_sub_f32_e32 v1, v1, v8
	v_add_f32_e32 v51, v13, v51
	v_exp_f32_e32 v1, v1
	v_sub_f32_e32 v4, v4, v8
	v_add_f32_e32 v51, v16, v51
	v_exp_f32_e32 v4, v4
	v_sub_f32_e32 v5, v5, v8
	v_add_f32_e32 v51, v17, v51
	v_exp_f32_e32 v5, v5
	v_sub_f32_e32 v2, v2, v8
	v_add_f32_e32 v51, v0, v51
	v_exp_f32_e32 v2, v2
	v_sub_f32_e32 v3, v3, v8
	v_add_f32_e32 v51, v1, v51
	v_exp_f32_e32 v3, v3
	v_sub_f32_e32 v6, v6, v8
	v_add_f32_e32 v51, v4, v51
	v_exp_f32_e32 v6, v6
	v_sub_f32_e32 v7, v7, v8
	v_add_f32_e32 v51, v5, v51
	v_exp_f32_e32 v7, v7
	v_add_f32_e32 v8, v2, v51
	v_add_f32_e32 v8, v3, v8
	v_add_f32_e32 v8, v6, v8
	v_add_f32_e32 v8, v7, v8
	ds_bpermute_b32 v9, v9, v8
	ds_read_b64_tr_b16 v[70:71], v124 offset:4352
	ds_read_b64_tr_b16 v[68:69], v124
	s_waitcnt lgkmcnt(2)
	v_add_f32_e32 v8, v8, v9
	ds_bpermute_b32 v9, v40, v8
	s_waitcnt lgkmcnt(0)
	v_add_f32_e32 v8, v8, v9
	v_rcp_f32_e32 v8, v8
	s_nop 0
	v_pk_mul_f32 v[66:67], v[102:103], v[8:9] op_sel_hi:[1,0]
	v_pk_mul_f32 v[64:65], v[100:101], v[8:9] op_sel_hi:[1,0]
	v_pk_mul_f32 v[74:75], v[140:141], v[8:9] op_sel_hi:[1,0]
	v_pk_mul_f32 v[76:77], v[104:105], v[8:9] op_sel_hi:[1,0]
	v_cvt_pk_bf16_f32 v64, v64, v65
	v_cvt_pk_bf16_f32 v65, v66, v67
	v_cvt_pk_bf16_f32 v66, v76, v77
	v_cvt_pk_bf16_f32 v67, v74, v75
	ds_read_b64_tr_b16 v[76:77], v124 offset:4384
	ds_read_b64_tr_b16 v[74:75], v124 offset:32
	ds_read_b64_tr_b16 v[78:79], v124 offset:64
	ds_read_b64_tr_b16 v[82:83], v124 offset:96
	ds_read_b64_tr_b16 v[80:81], v124 offset:4416
	ds_read_b64_tr_b16 v[84:85], v124 offset:4448
	ds_read_b64_tr_b16 v[90:91], v124 offset:128
	ds_read_b64_tr_b16 v[92:93], v124 offset:4480
	ds_read_b64_tr_b16 v[100:101], v124 offset:4512
	ds_read_b64_tr_b16 v[98:99], v124 offset:160
	ds_read_b64_tr_b16 v[102:103], v124 offset:192
	ds_read_b64_tr_b16 v[140:141], v124 offset:224
	ds_read_b64_tr_b16 v[104:105], v124 offset:4544
	ds_read_b64_tr_b16 v[142:143], v124 offset:4576
	v_mfma_f32_16x16x32_bf16 v[68:71], v[68:71], v[64:67], 0
	s_waitcnt lgkmcnt(12)
	v_mfma_f32_16x16x32_bf16 v[74:77], v[74:77], v[64:67], 0
	s_waitcnt lgkmcnt(9)
	v_mfma_f32_16x16x32_bf16 v[78:81], v[78:81], v[64:67], 0
	s_waitcnt lgkmcnt(8)
	v_mfma_f32_16x16x32_bf16 v[82:85], v[82:85], v[64:67], 0
	s_waitcnt lgkmcnt(6)
	v_mfma_f32_16x16x32_bf16 v[90:93], v[90:93], v[64:67], 0
	s_waitcnt lgkmcnt(4)
	v_mfma_f32_16x16x32_bf16 v[98:101], v[98:101], v[64:67], 0
	s_waitcnt lgkmcnt(1)
	v_mfma_f32_16x16x32_bf16 v[102:105], v[102:105], v[64:67], 0
	s_waitcnt lgkmcnt(0)
	v_mfma_f32_16x16x32_bf16 v[64:67], v[140:143], v[64:67], 0
	v_mul_f32_e64 v88, v88, v8
	v_mul_f32_e64 v89, v89, v8
	v_pk_mul_f32 v[140:141], v[96:97], v[8:9] op_sel_hi:[1,0]
	v_pk_mul_f32 v[142:143], v[86:87], v[8:9] op_sel_hi:[1,0]
	v_cvt_pk_bf16_f32 v87, v88, v89
	ds_read_b64_tr_b16 v[96:97], v124 offset:13056
	ds_read_b64_tr_b16 v[94:95], v124 offset:8704
	v_cvt_pk_bf16_f32 v88, v142, v143
	v_cvt_pk_bf16_f32 v89, v140, v141
	ds_read_b64_tr_b16 v[142:143], v124 offset:13088
	ds_read_b64_tr_b16 v[140:141], v124 offset:8736
	ds_read_b64_tr_b16 v[144:145], v124 offset:8768
	ds_read_b64_tr_b16 v[148:149], v124 offset:8800
	ds_read_b64_tr_b16 v[146:147], v124 offset:13120
	ds_read_b64_tr_b16 v[150:151], v124 offset:13152
	v_pk_mul_f32 v[72:73], v[72:73], v[8:9] op_sel_hi:[1,0]
	s_nop 0
	v_cvt_pk_bf16_f32 v86, v72, v73
	s_waitcnt lgkmcnt(6)
	s_nop 0
	v_mfma_f32_16x16x32_bf16 v[68:71], v[94:97], v[86:89], v[68:71]
	ds_read_b64_tr_b16 v[94:95], v124 offset:8832
	ds_read_b64_tr_b16 v[96:97], v124 offset:13184
	s_waitcnt lgkmcnt(6)
	v_mfma_f32_16x16x32_bf16 v[72:75], v[140:143], v[86:89], v[74:77]
	s_waitcnt lgkmcnt(3)
	v_mfma_f32_16x16x32_bf16 v[76:79], v[144:147], v[86:89], v[78:81]
	s_waitcnt lgkmcnt(2)
	v_mfma_f32_16x16x32_bf16 v[80:83], v[148:151], v[86:89], v[82:85]
	ds_read_b64_tr_b16 v[142:143], v124 offset:13216
	ds_read_b64_tr_b16 v[140:141], v124 offset:8864
	ds_read_b64_tr_b16 v[144:145], v124 offset:8896
	ds_read_b64_tr_b16 v[148:149], v124 offset:8928
	ds_read_b64_tr_b16 v[146:147], v124 offset:13248
	ds_read_b64_tr_b16 v[150:151], v124 offset:13280
	s_waitcnt lgkmcnt(6)
	v_mfma_f32_16x16x32_bf16 v[90:93], v[94:97], v[86:89], v[90:93]
	s_waitcnt lgkmcnt(4)
	v_mfma_f32_16x16x32_bf16 v[94:97], v[140:143], v[86:89], v[98:101]
	s_waitcnt lgkmcnt(1)
	v_mfma_f32_16x16x32_bf16 v[98:101], v[144:147], v[86:89], v[102:105]
	s_waitcnt lgkmcnt(0)
	v_mfma_f32_16x16x32_bf16 v[64:67], v[148:151], v[86:89], v[64:67]
	v_mul_f32_e64 v60, v60, v8
	v_mul_f32_e64 v61, v61, v8
	v_pk_mul_f32 v[56:57], v[56:57], v[8:9] op_sel_hi:[1,0]
	v_pk_mul_f32 v[84:85], v[62:63], v[8:9] op_sel_hi:[1,0]
	v_pk_mul_f32 v[58:59], v[58:59], v[8:9] op_sel_hi:[1,0]
	v_cvt_pk_bf16_f32 v56, v56, v57
	v_cvt_pk_bf16_f32 v57, v60, v61
	ds_read_b64_tr_b16 v[62:63], v124 offset:21760
	ds_read_b64_tr_b16 v[60:61], v124 offset:17408
	v_cvt_pk_bf16_f32 v58, v58, v59
	v_cvt_pk_bf16_f32 v59, v84, v85
	ds_read_b64_tr_b16 v[86:87], v124 offset:21792
	ds_read_b64_tr_b16 v[84:85], v124 offset:17440
	ds_read_b64_tr_b16 v[102:103], v124 offset:17472
	ds_read_b64_tr_b16 v[140:141], v124 offset:17504
	ds_read_b64_tr_b16 v[104:105], v124 offset:21824
	ds_read_b64_tr_b16 v[142:143], v124 offset:21856
	s_waitcnt lgkmcnt(6)
	v_mfma_f32_16x16x32_bf16 v[60:63], v[60:63], v[56:59], v[68:71]
	s_waitcnt lgkmcnt(4)
	v_mfma_f32_16x16x32_bf16 v[68:71], v[84:87], v[56:59], v[72:75]
	s_waitcnt lgkmcnt(1)
	v_mfma_f32_16x16x32_bf16 v[72:75], v[102:105], v[56:59], v[76:79]
	s_nop 2
	ds_read_b64_tr_b16 v[76:77], v124 offset:17536
	ds_read_b64_tr_b16 v[78:79], v124 offset:21888
	s_waitcnt lgkmcnt(2)
	v_mfma_f32_16x16x32_bf16 v[80:83], v[140:143], v[56:59], v[80:83]
	ds_read_b64_tr_b16 v[86:87], v124 offset:21920
	ds_read_b64_tr_b16 v[84:85], v124 offset:17568
	ds_read_b64_tr_b16 v[102:103], v124 offset:17600
	ds_read_b64_tr_b16 v[140:141], v124 offset:17632
	ds_read_b64_tr_b16 v[104:105], v124 offset:21952
	ds_read_b64_tr_b16 v[142:143], v124 offset:21984
	s_waitcnt lgkmcnt(6)
	v_mfma_f32_16x16x32_bf16 v[76:79], v[76:79], v[56:59], v[90:93]
	s_waitcnt lgkmcnt(4)
	v_mfma_f32_16x16x32_bf16 v[84:87], v[84:87], v[56:59], v[94:97]
	s_waitcnt lgkmcnt(1)
	v_mfma_f32_16x16x32_bf16 v[88:91], v[102:105], v[56:59], v[98:101]
	s_waitcnt lgkmcnt(0)
	v_mfma_f32_16x16x32_bf16 v[56:59], v[140:143], v[56:59], v[64:67]
	s_nop 2
	ds_read_b64_tr_b16 v[66:67], v124 offset:30464
	ds_read_b64_tr_b16 v[64:65], v124 offset:26112
	ds_read_b64_tr_b16 v[94:95], v124 offset:30496
	ds_read_b64_tr_b16 v[92:93], v124 offset:26144
	ds_read_b64_tr_b16 v[96:97], v124 offset:26176
	ds_read_b64_tr_b16 v[100:101], v124 offset:26208
	ds_read_b64_tr_b16 v[98:99], v124 offset:30528
	ds_read_b64_tr_b16 v[102:103], v124 offset:30560
	v_pk_mul_f32 v[38:39], v[38:39], v[8:9] op_sel_hi:[1,0]
	v_pk_mul_f32 v[34:35], v[34:35], v[8:9] op_sel_hi:[1,0]
	v_pk_mul_f32 v[54:55], v[54:55], v[8:9] op_sel_hi:[1,0]
	v_pk_mul_f32 v[36:37], v[36:37], v[8:9] op_sel_hi:[1,0]
	v_cvt_pk_bf16_f32 v34, v34, v35
	v_cvt_pk_bf16_f32 v35, v38, v39
	v_cvt_pk_bf16_f32 v36, v36, v37
	v_cvt_pk_bf16_f32 v37, v54, v55
	s_waitcnt lgkmcnt(6)
	s_nop 0
	v_mfma_f32_16x16x32_bf16 v[60:63], v[64:67], v[34:37], v[60:63]
	s_waitcnt lgkmcnt(4)
	v_mfma_f32_16x16x32_bf16 v[64:67], v[92:95], v[34:37], v[68:71]
	s_waitcnt lgkmcnt(1)
	v_mfma_f32_16x16x32_bf16 v[68:71], v[96:99], v[34:37], v[72:75]
	s_nop 2
	ds_read_b64_tr_b16 v[72:73], v124 offset:26240
	ds_read_b64_tr_b16 v[74:75], v124 offset:30592
	s_waitcnt lgkmcnt(2)
	v_mfma_f32_16x16x32_bf16 v[80:83], v[100:103], v[34:37], v[80:83]
	ds_read_b64_tr_b16 v[94:95], v124 offset:30624
	ds_read_b64_tr_b16 v[92:93], v124 offset:26272
	ds_read_b64_tr_b16 v[96:97], v124 offset:26304
	ds_read_b64_tr_b16 v[100:101], v124 offset:26336
	ds_read_b64_tr_b16 v[98:99], v124 offset:30656
	ds_read_b64_tr_b16 v[102:103], v124 offset:30688
	s_waitcnt lgkmcnt(6)
	v_mfma_f32_16x16x32_bf16 v[72:75], v[72:75], v[34:37], v[76:79]
	s_waitcnt lgkmcnt(4)
	v_mfma_f32_16x16x32_bf16 v[76:79], v[92:95], v[34:37], v[84:87]
	s_waitcnt lgkmcnt(1)
	v_mfma_f32_16x16x32_bf16 v[84:87], v[96:99], v[34:37], v[88:91]
	s_waitcnt lgkmcnt(0)
	v_mfma_f32_16x16x32_bf16 v[34:37], v[100:103], v[34:37], v[56:59]
	v_mul_f32_e64 v30, v30, v8
	v_mul_f32_e64 v31, v31, v8
	v_pk_mul_f32 v[26:27], v[26:27], v[8:9] op_sel_hi:[1,0]
	v_pk_mul_f32 v[38:39], v[32:33], v[8:9] op_sel_hi:[1,0]
	v_cvt_pk_bf16_f32 v26, v26, v27
	v_cvt_pk_bf16_f32 v27, v30, v31
	ds_read_b64_tr_b16 v[32:33], v124 offset:39168
	ds_read_b64_tr_b16 v[30:31], v124 offset:34816
	ds_read_b64_tr_b16 v[56:57], v124 offset:39200
	ds_read_b64_tr_b16 v[54:55], v124 offset:34848
	ds_read_b64_tr_b16 v[88:89], v124 offset:34880
	ds_read_b64_tr_b16 v[92:93], v124 offset:34912
	ds_read_b64_tr_b16 v[90:91], v124 offset:39232
	ds_read_b64_tr_b16 v[94:95], v124 offset:39264
	v_pk_mul_f32 v[28:29], v[28:29], v[8:9] op_sel_hi:[1,0]
	s_nop 0
	v_cvt_pk_bf16_f32 v28, v28, v29
	v_cvt_pk_bf16_f32 v29, v38, v39
	s_waitcnt lgkmcnt(6)
	s_nop 0
	v_mfma_f32_16x16x32_bf16 v[30:33], v[30:33], v[26:29], v[60:63]
	s_waitcnt lgkmcnt(4)
	v_mfma_f32_16x16x32_bf16 v[54:57], v[54:57], v[26:29], v[64:67]
	s_nop 0
	ds_read_b64_tr_b16 v[62:63], v124 offset:34944
	s_nop 0
	ds_read_b64_tr_b16 v[64:65], v124 offset:39296
	s_waitcnt lgkmcnt(3)
	v_mfma_f32_16x16x32_bf16 v[58:61], v[88:91], v[26:29], v[68:71]
	s_waitcnt lgkmcnt(2)
	v_mfma_f32_16x16x32_bf16 v[66:69], v[92:95], v[26:29], v[80:83]
	s_nop 2
	ds_read_b64_tr_b16 v[82:83], v124 offset:39328
	ds_read_b64_tr_b16 v[80:81], v124 offset:34976
	ds_read_b64_tr_b16 v[88:89], v124 offset:35008
	ds_read_b64_tr_b16 v[92:93], v124 offset:35040
	ds_read_b64_tr_b16 v[90:91], v124 offset:39360
	ds_read_b64_tr_b16 v[94:95], v124 offset:39392
	s_waitcnt lgkmcnt(6)
	v_mfma_f32_16x16x32_bf16 v[62:65], v[62:65], v[26:29], v[72:75]
	s_waitcnt lgkmcnt(4)
	v_mfma_f32_16x16x32_bf16 v[70:73], v[80:83], v[26:29], v[76:79]
	s_waitcnt lgkmcnt(1)
	v_mfma_f32_16x16x32_bf16 v[74:77], v[88:91], v[26:29], v[84:87]
	s_waitcnt lgkmcnt(0)
	v_mfma_f32_16x16x32_bf16 v[26:29], v[92:95], v[26:29], v[34:37]
	v_mul_f32_e64 v22, v22, v8
	v_mul_f32_e64 v23, v23, v8
	v_pk_mul_f32 v[18:19], v[18:19], v[8:9] op_sel_hi:[1,0]
	v_pk_mul_f32 v[34:35], v[24:25], v[8:9] op_sel_hi:[1,0]
	v_pk_mul_f32 v[20:21], v[20:21], v[8:9] op_sel_hi:[1,0]
	v_cvt_pk_bf16_f32 v18, v18, v19
	v_cvt_pk_bf16_f32 v19, v22, v23
	ds_read_b64_tr_b16 v[24:25], v124 offset:47872
	ds_read_b64_tr_b16 v[22:23], v124 offset:43520
	v_cvt_pk_bf16_f32 v20, v20, v21
	v_cvt_pk_bf16_f32 v21, v34, v35
	ds_read_b64_tr_b16 v[36:37], v124 offset:47904
	ds_read_b64_tr_b16 v[34:35], v124 offset:43552
	ds_read_b64_tr_b16 v[78:79], v124 offset:43584
	ds_read_b64_tr_b16 v[82:83], v124 offset:43616
	ds_read_b64_tr_b16 v[80:81], v124 offset:47936
	ds_read_b64_tr_b16 v[84:85], v124 offset:47968
	s_waitcnt lgkmcnt(6)
	v_mfma_f32_16x16x32_bf16 v[22:25], v[22:25], v[18:21], v[30:33]
	s_waitcnt lgkmcnt(4)
	v_mfma_f32_16x16x32_bf16 v[30:33], v[34:37], v[18:21], v[54:57]
	s_nop 2
	ds_read_b64_tr_b16 v[54:55], v124 offset:43648
	ds_read_b64_tr_b16 v[56:57], v124 offset:48000
	s_waitcnt lgkmcnt(3)
	v_mfma_f32_16x16x32_bf16 v[34:37], v[78:81], v[18:21], v[58:61]
	s_waitcnt lgkmcnt(2)
	v_mfma_f32_16x16x32_bf16 v[58:61], v[82:85], v[18:21], v[66:69]
	s_nop 2
	ds_read_b64_tr_b16 v[68:69], v124 offset:48032
	ds_read_b64_tr_b16 v[66:67], v124 offset:43680
	ds_read_b64_tr_b16 v[78:79], v124 offset:43712
	ds_read_b64_tr_b16 v[82:83], v124 offset:43744
	ds_read_b64_tr_b16 v[80:81], v124 offset:48064
	ds_read_b64_tr_b16 v[84:85], v124 offset:48096
	s_waitcnt lgkmcnt(6)
	v_mfma_f32_16x16x32_bf16 v[54:57], v[54:57], v[18:21], v[62:65]
	s_waitcnt lgkmcnt(4)
	v_mfma_f32_16x16x32_bf16 v[62:65], v[66:69], v[18:21], v[70:73]
	s_waitcnt lgkmcnt(1)
	v_mfma_f32_16x16x32_bf16 v[66:69], v[78:81], v[18:21], v[74:77]
	s_waitcnt lgkmcnt(0)
	v_mfma_f32_16x16x32_bf16 v[18:21], v[82:85], v[18:21], v[26:29]
	v_mul_f32_e64 v14, v14, v8
	v_mul_f32_e64 v15, v15, v8
	v_pk_mul_f32 v[10:11], v[10:11], v[8:9] op_sel_hi:[1,0]
	v_pk_mul_f32 v[26:27], v[16:17], v[8:9] op_sel_hi:[1,0]
	v_cvt_pk_bf16_f32 v10, v10, v11
	v_cvt_pk_bf16_f32 v11, v14, v15
	ds_read_b64_tr_b16 v[16:17], v124 offset:56576
	ds_read_b64_tr_b16 v[14:15], v124 offset:52224
	v_pk_mul_f32 v[12:13], v[12:13], v[8:9] op_sel_hi:[1,0]
	s_nop 0
	v_cvt_pk_bf16_f32 v12, v12, v13
	v_cvt_pk_bf16_f32 v13, v26, v27
	ds_read_b64_tr_b16 v[28:29], v124 offset:56608
	ds_read_b64_tr_b16 v[26:27], v124 offset:52256
	ds_read_b64_tr_b16 v[70:71], v124 offset:52288
	ds_read_b64_tr_b16 v[74:75], v124 offset:52320
	ds_read_b64_tr_b16 v[72:73], v124 offset:56640
	ds_read_b64_tr_b16 v[76:77], v124 offset:56672
	s_waitcnt lgkmcnt(6)
	v_mfma_f32_16x16x32_bf16 v[14:17], v[14:17], v[10:13], v[22:25]
	s_waitcnt lgkmcnt(4)
	v_mfma_f32_16x16x32_bf16 v[22:25], v[26:29], v[10:13], v[30:33]
	s_nop 2
	ds_read_b64_tr_b16 v[30:31], v124 offset:52352
	ds_read_b64_tr_b16 v[32:33], v124 offset:56704
	s_waitcnt lgkmcnt(3)
	v_mfma_f32_16x16x32_bf16 v[26:29], v[70:73], v[10:13], v[34:37]
	s_waitcnt lgkmcnt(2)
	v_mfma_f32_16x16x32_bf16 v[34:37], v[74:77], v[10:13], v[58:61]
	s_nop 2
	ds_read_b64_tr_b16 v[60:61], v124 offset:56736
	ds_read_b64_tr_b16 v[58:59], v124 offset:52384
	ds_read_b64_tr_b16 v[70:71], v124 offset:52416
	ds_read_b64_tr_b16 v[74:75], v124 offset:52448
	ds_read_b64_tr_b16 v[72:73], v124 offset:56768
	ds_read_b64_tr_b16 v[76:77], v124 offset:56800
	s_waitcnt lgkmcnt(6)
	v_mfma_f32_16x16x32_bf16 v[30:33], v[30:33], v[10:13], v[54:57]
	s_waitcnt lgkmcnt(4)
	v_mfma_f32_16x16x32_bf16 v[54:57], v[58:61], v[10:13], v[62:65]
	s_waitcnt lgkmcnt(1)
	v_mfma_f32_16x16x32_bf16 v[58:61], v[70:73], v[10:13], v[66:69]
	s_waitcnt lgkmcnt(0)
	v_mfma_f32_16x16x32_bf16 v[62:65], v[74:77], v[10:13], v[18:21]
	v_mul_f32_e64 v4, v4, v8
	v_mul_f32_e64 v5, v5, v8
	v_pk_mul_f32 v[0:1], v[0:1], v[8:9] op_sel_hi:[1,0]
	v_pk_mul_f32 v[6:7], v[6:7], v[8:9] op_sel_hi:[1,0]
	v_pk_mul_f32 v[8:9], v[2:3], v[8:9] op_sel_hi:[1,0]
	v_cvt_pk_bf16_f32 v66, v0, v1
	v_cvt_pk_bf16_f32 v67, v4, v5
	ds_read_b64_tr_b16 v[2:3], v124 offset:65280
	ds_read_b64_tr_b16 v[0:1], v124 offset:60928
	v_cvt_pk_bf16_f32 v69, v6, v7
	ds_read_b64_tr_b16 v[6:7], v124 offset:65312
	ds_read_b64_tr_b16 v[4:5], v124 offset:60960
	ds_read_b64_tr_b16 v[18:19], v124 offset:60992
	ds_read_b64_tr_b16 v[70:71], v124 offset:61024
	ds_read_b64_tr_b16 v[20:21], v124 offset:65344
	ds_read_b64_tr_b16 v[72:73], v124 offset:65376
	v_cvt_pk_bf16_f32 v68, v8, v9
	s_waitcnt lgkmcnt(6)
	s_nop 0
	v_mfma_f32_16x16x32_bf16 v[12:15], v[0:3], v[66:69], v[14:17]
	s_waitcnt lgkmcnt(4)
	v_mfma_f32_16x16x32_bf16 v[8:11], v[4:7], v[66:69], v[22:25]
	s_waitcnt lgkmcnt(1)
	v_mfma_f32_16x16x32_bf16 v[0:3], v[18:21], v[66:69], v[26:29]
	ds_read_b64_tr_b16 v[16:17], v124 offset:61056
	ds_read_b64_tr_b16 v[18:19], v124 offset:65408
	s_waitcnt lgkmcnt(2)
	v_mfma_f32_16x16x32_bf16 v[4:7], v[70:73], v[66:69], v[34:37]
	ds_read_b64_tr_b16 v[22:23], v124 offset:65440
	ds_read_b64_tr_b16 v[20:21], v124 offset:61088
	s_nop 0
	ds_read_b64_tr_b16 v[34:35], v124 offset:61120
	ds_read_b64_tr_b16 v[70:71], v124 offset:61152
	ds_read_b64_tr_b16 v[36:37], v124 offset:65472
	ds_read_b64_tr_b16 v[72:73], v124 offset:65504
	s_waitcnt lgkmcnt(6)
	v_mfma_f32_16x16x32_bf16 v[28:31], v[16:19], v[66:69], v[30:33]
	s_waitcnt lgkmcnt(4)
	v_mfma_f32_16x16x32_bf16 v[24:27], v[20:23], v[66:69], v[54:57]
	s_waitcnt lgkmcnt(1)
	v_mfma_f32_16x16x32_bf16 v[16:19], v[34:37], v[66:69], v[58:61]
	s_waitcnt lgkmcnt(0)
	v_mfma_f32_16x16x32_bf16 v[20:23], v[70:73], v[66:69], v[62:65]
	s_and_b64 exec, exec, s[6:7]
	s_cbranch_execz .LBB0_1056
	v_lshlrev_b32_e32 v32, 9, v53
	v_lshlrev_b32_e32 v40, 1, v32
	v_lshl_add_u64 v[32:33], s[12:13], 0, v[40:41]
	v_lshl_add_u64 v[32:33], v[32:33], 0, s[2:3]
	v_mov_b32_e32 v53, v41
	v_lshl_add_u64 v[32:33], v[32:33], 0, v[52:53]
	v_cvt_pk_bf16_f32 v0, v0, v1
	v_cvt_pk_bf16_f32 v1, v2, v3
	global_store_dwordx2 v[32:33], v[0:1], off offset:64
	v_cvt_pk_bf16_f32 v0, v4, v5
	v_cvt_pk_bf16_f32 v1, v6, v7
	global_store_dwordx2 v[32:33], v[0:1], off offset:96
	v_cvt_pk_bf16_f32 v0, v28, v29
	v_cvt_pk_bf16_f32 v1, v30, v31
	global_store_dwordx2 v[32:33], v[0:1], off offset:128
	v_cvt_pk_bf16_f32 v0, v24, v25
	v_cvt_pk_bf16_f32 v1, v26, v27
	global_store_dwordx2 v[32:33], v[0:1], off offset:160
	v_cvt_pk_bf16_f32 v0, v16, v17
	v_cvt_pk_bf16_f32 v1, v18, v19
	v_cvt_pk_bf16_f32 v12, v12, v13
	v_cvt_pk_bf16_f32 v13, v14, v15
	v_cvt_pk_bf16_f32 v8, v8, v9
	v_cvt_pk_bf16_f32 v9, v10, v11
	global_store_dwordx2 v[32:33], v[0:1], off offset:192
	v_cvt_pk_bf16_f32 v0, v20, v21
	v_cvt_pk_bf16_f32 v1, v22, v23
	global_store_dwordx2 v[32:33], v[12:13], off
	global_store_dwordx2 v[32:33], v[8:9], off offset:32
	global_store_dwordx2 v[32:33], v[0:1], off offset:224
